# fast loop: exps balanced per MFMA gap (7 of a tile's exps delayed into the next step's phase A before their consumers, 25 dealt 4,3,3.. over phase B; peeled first step; exit stub finishes pending exps
# speedup vs baseline: 1.0128x; 1.0128x over previous
; #define WAIT_BAR(N) asm volatile("s_waitcnt vmcnt(" #N ") lgkmcnt(0)\n\ts_barrier":::"memory")
;   #define RESC() do{ if(resc){ asm volatile("s_waitcnt lgkmcnt(0)":::"memory"); \
;       _Pragma("unroll") for(int d_=0;d_<2;++d_) _Pragma("unroll") for(int r=0;r<16;++r)o[d_][r]*=wsf[crow(r,hi)]; } }while(0)
;   #define ROT() do{sl_prev=sl_cur;sl_cur=sl_next;sl_next=(sl_next==(NSLOT-1)*SLOTB)?0:sl_next+SLOTB;}while(0)
;     ...
;   int t=1;
;     ...
;   for(;t+5<NT;t+=2){
;     STEP(pB0,pB1,pA0,pA1,t,true,true,true);     WAIT_BAR(2); RESC(); ROT();
.Lfb_pre:
	v_lshl_add_u64 v[188:189], v[188:189], 0, s[20:21]
	v_lshl_add_u64 v[186:187], v[186:187], 0, s[20:21]
	s_mov_b64 s[0:1], 0x5d60e00
	v_lshl_add_u64 v[188:189], v[188:189], 0, s[0:1]
	s_mov_b64 s[0:1], 0x5cb1200
	v_lshl_add_u64 v[186:187], v[186:187], 0, s[0:1]
	s_nop 0
	v_readfirstlane_b32 s2, v188
	v_readfirstlane_b32 s3, v189
	v_readfirstlane_b32 s26, v186
	v_readfirstlane_b32 s27, v187
	s_nop 1
	v_subrev_u32_e32 v188, s2, v188
	v_subrev_u32_e32 v186, s26, v186
	s_mov_b32 s0, 0
	s_bitcmp1_b32 s32, 8
	s_cbranch_scc1 .Lfb_odd_entry
	s_branch .Lfb_even_entry
.Lfb_even_entry:
	v_mfma_f32_32x32x16_bf16 v[96:111], v[174:177], v[134:137], v[32:47]
	v_add_u32_e32 v183, s0, v211
	ds_read_b64_tr_b16 v[178:179], v183 offset:24576
	ds_read_b64_tr_b16 v[180:181], v183 offset:25088
	v_add_f32_e32 v222, v64, v222
	v_add_f32_e32 v222, v65, v222
	v_add_f32_e32 v222, v66, v222
	v_add_f32_e32 v222, v67, v222
	v_add_f32_e32 v222, v68, v222
	v_add_f32_e32 v222, v69, v222
	v_cvt_pk_bf16_f32 v142, v64, v65
	v_cvt_pk_bf16_f32 v143, v66, v67
	ds_read_b64_tr_b16 v[174:175], v183 offset:28672
	ds_read_b64_tr_b16 v[176:177], v183 offset:29184
	v_add_f32_e32 v222, v70, v222
	v_mfma_f32_32x32x16_bf16 v[80:95], v[170:173], v[134:137], v[32:47]
	v_add_f32_e32 v222, v71, v222
	v_add_f32_e32 v222, v72, v222
	v_add_f32_e32 v222, v73, v222
	v_cvt_pk_bf16_f32 v144, v68, v69
	v_cvt_pk_bf16_f32 v145, v70, v71
	ds_read_b64_tr_b16 v[64:65], v183 offset:25600
	ds_read_b64_tr_b16 v[66:67], v183 offset:26112
	v_mfma_f32_32x32x16_bf16 v[96:111], v[166:169], v[122:125], v[96:111]
	v_add_f32_e32 v222, v74, v222
	v_add_f32_e32 v222, v75, v222
	v_add_f32_e32 v222, v76, v222
	v_add_f32_e32 v222, v77, v222
	v_cvt_pk_bf16_f32 v138, v72, v73
	v_cvt_pk_bf16_f32 v139, v74, v75
	ds_read_b64_tr_b16 v[68:69], v183 offset:29696
	ds_read_b64_tr_b16 v[70:71], v183 offset:30208
	v_mfma_f32_32x32x16_bf16 v[80:95], v[162:165], v[122:125], v[80:95]
	v_add_f32_e32 v222, v78, v222
	v_add_f32_e32 v222, v79, v222
	v_cvt_pk_bf16_f32 v140, v76, v77
	v_cvt_pk_bf16_f32 v141, v78, v79
	ds_read_b64_tr_b16 v[72:73], v183 offset:26624
	ds_read_b64_tr_b16 v[74:75], v183 offset:27136
	v_mfma_f32_32x32x16_bf16 v[96:111], v[158:161], v[118:121], v[96:111]
	v_cvt_pk_bf16_f32 v130, v48, v49
	v_cvt_pk_bf16_f32 v131, v50, v51
	ds_read_b64_tr_b16 v[48:49], v183 offset:30720
	ds_read_b64_tr_b16 v[50:51], v183 offset:31232
	v_mfma_f32_32x32x16_bf16 v[80:95], v[154:157], v[118:121], v[80:95]
	v_cvt_pk_bf16_f32 v132, v52, v53
	v_cvt_pk_bf16_f32 v133, v54, v55
	ds_read_b64_tr_b16 v[52:53], v183 offset:27648
	ds_read_b64_tr_b16 v[54:55], v183 offset:28160
	v_mfma_f32_32x32x16_bf16 v[96:111], v[150:153], v[114:117], v[96:111]
	v_cvt_pk_bf16_f32 v126, v56, v57
	v_cvt_pk_bf16_f32 v127, v58, v59
	ds_read_b64_tr_b16 v[56:57], v183 offset:31744
	ds_read_b64_tr_b16 v[58:59], v183 offset:32256
	v_mfma_f32_32x32x16_bf16 v[80:95], v[146:149], v[114:117], v[80:95]
	v_cvt_pk_bf16_f32 v128, v60, v61
	v_cvt_pk_bf16_f32 v129, v62, v63
	s_add_i32 m0, s24, s69
	s_nop 0
	global_load_lds_dwordx4 v188, s[2:3]
	s_add_i32 m0, s13, s70
	s_add_u32 s2, s2, 0x58000
	global_load_lds_dwordx4 v186, s[26:27]
	s_addc_u32 s3, s3, 0
	s_add_u32 s26, s26, 0x58000
	s_addc_u32 s27, s27, 0
	s_waitcnt lgkmcnt(8)
	v_mfma_f32_32x32x16_bf16 v[16:31], v[142:145], v[178:181], v[16:31]
	v_exp_f32_e32 v96, v96
	v_exp_f32_e32 v97, v97
	v_exp_f32_e32 v98, v98
	v_exp_f32_e32 v99, v99
	v_mfma_f32_32x32x16_bf16 v[0:15], v[142:145], v[174:177], v[0:15]
	v_exp_f32_e32 v100, v100
	v_exp_f32_e32 v101, v101
	v_exp_f32_e32 v102, v102
	v_add_u32_e32 v76, s13, v210
	ds_read_b128 v[60:63], v76
	ds_read_b128 v[174:177], v76 offset:512
	v_mfma_f32_32x32x16_bf16 v[16:31], v[138:141], v[64:67], v[16:31]
	v_exp_f32_e32 v103, v103
	v_exp_f32_e32 v104, v104
	v_exp_f32_e32 v105, v105
	ds_read_b128 v[178:181], v76 offset:2048
	ds_read_b128 v[170:173], v76 offset:2560
	v_mfma_f32_32x32x16_bf16 v[0:15], v[138:141], v[68:71], v[0:15]
	v_exp_f32_e32 v106, v106
	v_exp_f32_e32 v107, v107
	v_exp_f32_e32 v108, v108
	ds_read_b128 v[166:169], v76 offset:4096
	ds_read_b128 v[162:165], v76 offset:4608
	s_waitcnt lgkmcnt(6)
	v_mfma_f32_32x32x16_bf16 v[16:31], v[130:133], v[72:75], v[16:31]
	v_exp_f32_e32 v109, v109
	v_exp_f32_e32 v110, v110
	v_exp_f32_e32 v111, v111
	ds_read_b128 v[158:161], v76 offset:6144
	ds_read_b128 v[154:157], v76 offset:6656
	v_mfma_f32_32x32x16_bf16 v[0:15], v[130:133], v[48:51], v[0:15]
	v_exp_f32_e32 v80, v80
	v_exp_f32_e32 v81, v81
	v_exp_f32_e32 v82, v82
	v_mfma_f32_32x32x16_bf16 v[16:31], v[126:129], v[52:55], v[16:31]
	v_exp_f32_e32 v83, v83
	v_exp_f32_e32 v84, v84
	v_exp_f32_e32 v85, v85
	v_mfma_f32_32x32x16_bf16 v[0:15], v[126:129], v[56:59], v[0:15]
	v_exp_f32_e32 v86, v86
	v_exp_f32_e32 v87, v87
	v_exp_f32_e32 v88, v88
	s_add_i32 s0, s13, 0x2000
	s_cmpk_lg_i32 s13, 0x4000
	s_cselect_b32 s72, s0, 0
	s_waitcnt vmcnt(2) lgkmcnt(0)
	s_barrier
	s_branch .Lfb_even_s2
.Lfb_even:
	v_mfma_f32_32x32x16_bf16 v[96:111], v[174:177], v[134:137], v[32:47]
	v_add_u32_e32 v183, s0, v211
	ds_read_b64_tr_b16 v[178:179], v183 offset:24576
	ds_read_b64_tr_b16 v[180:181], v183 offset:25088
	v_add_f32_e32 v222, v64, v222
	v_add_f32_e32 v222, v65, v222
	v_add_f32_e32 v222, v66, v222
	v_add_f32_e32 v222, v67, v222
	v_add_f32_e32 v222, v68, v222
	v_add_f32_e32 v222, v69, v222
	v_cvt_pk_bf16_f32 v142, v64, v65
	v_cvt_pk_bf16_f32 v143, v66, v67
	ds_read_b64_tr_b16 v[174:175], v183 offset:28672
	ds_read_b64_tr_b16 v[176:177], v183 offset:29184
	v_add_f32_e32 v222, v70, v222
	v_mfma_f32_32x32x16_bf16 v[80:95], v[170:173], v[134:137], v[32:47]
	v_add_f32_e32 v222, v71, v222
	v_add_f32_e32 v222, v72, v222
	v_add_f32_e32 v222, v73, v222
	v_cvt_pk_bf16_f32 v144, v68, v69
	v_cvt_pk_bf16_f32 v145, v70, v71
	ds_read_b64_tr_b16 v[64:65], v183 offset:25600
	ds_read_b64_tr_b16 v[66:67], v183 offset:26112
	v_mfma_f32_32x32x16_bf16 v[96:111], v[166:169], v[122:125], v[96:111]
	v_add_f32_e32 v222, v74, v222
	v_add_f32_e32 v222, v75, v222
	v_add_f32_e32 v222, v76, v222
	v_add_f32_e32 v222, v77, v222
	v_cvt_pk_bf16_f32 v138, v72, v73
	v_cvt_pk_bf16_f32 v139, v74, v75
	ds_read_b64_tr_b16 v[68:69], v183 offset:29696
	ds_read_b64_tr_b16 v[70:71], v183 offset:30208
	v_mfma_f32_32x32x16_bf16 v[80:95], v[162:165], v[122:125], v[80:95]
	v_exp_f32_e32 v57, v57
	v_add_f32_e32 v222, v78, v222
	v_add_f32_e32 v222, v79, v222
	v_cvt_pk_bf16_f32 v140, v76, v77
	v_cvt_pk_bf16_f32 v141, v78, v79
	ds_read_b64_tr_b16 v[72:73], v183 offset:26624
	ds_read_b64_tr_b16 v[74:75], v183 offset:27136
	v_mfma_f32_32x32x16_bf16 v[96:111], v[158:161], v[118:121], v[96:111]
	v_exp_f32_e32 v58, v58
	v_exp_f32_e32 v59, v59
	v_cvt_pk_bf16_f32 v130, v48, v49
	v_cvt_pk_bf16_f32 v131, v50, v51
	ds_read_b64_tr_b16 v[48:49], v183 offset:30720
	ds_read_b64_tr_b16 v[50:51], v183 offset:31232
	v_mfma_f32_32x32x16_bf16 v[80:95], v[154:157], v[118:121], v[80:95]
	v_exp_f32_e32 v60, v60
	v_exp_f32_e32 v61, v61
	v_cvt_pk_bf16_f32 v132, v52, v53
	v_cvt_pk_bf16_f32 v133, v54, v55
	ds_read_b64_tr_b16 v[52:53], v183 offset:27648
	ds_read_b64_tr_b16 v[54:55], v183 offset:28160
	v_mfma_f32_32x32x16_bf16 v[96:111], v[150:153], v[114:117], v[96:111]
	v_exp_f32_e32 v62, v62
	v_exp_f32_e32 v63, v63
	v_cvt_pk_bf16_f32 v126, v56, v57
	v_cvt_pk_bf16_f32 v127, v58, v59
	ds_read_b64_tr_b16 v[56:57], v183 offset:31744
	ds_read_b64_tr_b16 v[58:59], v183 offset:32256
	v_mfma_f32_32x32x16_bf16 v[80:95], v[146:149], v[114:117], v[80:95]
	v_cvt_pk_bf16_f32 v128, v60, v61
	v_cvt_pk_bf16_f32 v129, v62, v63
	s_add_i32 m0, s24, s69
	s_nop 0
	global_load_lds_dwordx4 v188, s[2:3]
	s_add_i32 m0, s13, s70
	s_add_u32 s2, s2, 0x58000
	global_load_lds_dwordx4 v186, s[26:27]
	s_addc_u32 s3, s3, 0
	s_add_u32 s26, s26, 0x58000
	s_addc_u32 s27, s27, 0
	s_waitcnt lgkmcnt(8)
	v_mfma_f32_32x32x16_bf16 v[16:31], v[142:145], v[178:181], v[16:31]
	v_exp_f32_e32 v96, v96
	v_exp_f32_e32 v97, v97
	v_exp_f32_e32 v98, v98
	v_exp_f32_e32 v99, v99
	v_mfma_f32_32x32x16_bf16 v[0:15], v[142:145], v[174:177], v[0:15]
	v_exp_f32_e32 v100, v100
	v_exp_f32_e32 v101, v101
	v_exp_f32_e32 v102, v102
	v_add_u32_e32 v76, s13, v210
	ds_read_b128 v[60:63], v76
	ds_read_b128 v[174:177], v76 offset:512
	v_mfma_f32_32x32x16_bf16 v[16:31], v[138:141], v[64:67], v[16:31]
	v_exp_f32_e32 v103, v103
	v_exp_f32_e32 v104, v104
	v_exp_f32_e32 v105, v105
	ds_read_b128 v[178:181], v76 offset:2048
	ds_read_b128 v[170:173], v76 offset:2560
	v_mfma_f32_32x32x16_bf16 v[0:15], v[138:141], v[68:71], v[0:15]
	v_exp_f32_e32 v106, v106
	v_exp_f32_e32 v107, v107
	v_exp_f32_e32 v108, v108
	ds_read_b128 v[166:169], v76 offset:4096
	ds_read_b128 v[162:165], v76 offset:4608
	s_waitcnt lgkmcnt(6)
	v_mfma_f32_32x32x16_bf16 v[16:31], v[130:133], v[72:75], v[16:31]
	v_exp_f32_e32 v109, v109
	v_exp_f32_e32 v110, v110
	v_exp_f32_e32 v111, v111
	ds_read_b128 v[158:161], v76 offset:6144
	ds_read_b128 v[154:157], v76 offset:6656
	v_mfma_f32_32x32x16_bf16 v[0:15], v[130:133], v[48:51], v[0:15]
	v_exp_f32_e32 v80, v80
	v_exp_f32_e32 v81, v81
	v_exp_f32_e32 v82, v82
	v_mfma_f32_32x32x16_bf16 v[16:31], v[126:129], v[52:55], v[16:31]
	v_exp_f32_e32 v83, v83
	v_exp_f32_e32 v84, v84
	v_exp_f32_e32 v85, v85
	v_mfma_f32_32x32x16_bf16 v[0:15], v[126:129], v[56:59], v[0:15]
	v_exp_f32_e32 v86, v86
	v_exp_f32_e32 v87, v87
	v_exp_f32_e32 v88, v88
	s_add_i32 s0, s13, 0x2000
	s_cmpk_lg_i32 s13, 0x4000
	s_cselect_b32 s72, s0, 0
	s_waitcnt vmcnt(2) lgkmcnt(0)
	s_barrier
; #define WAIT_BAR(N) asm volatile("s_waitcnt vmcnt(" #N ") lgkmcnt(0)\n\ts_barrier":::"memory")
;   #define RESC() do{ if(resc){ asm volatile("s_waitcnt lgkmcnt(0)":::"memory"); \
;       _Pragma("unroll") for(int d_=0;d_<2;++d_) _Pragma("unroll") for(int r=0;r<16;++r)o[d_][r]*=wsf[crow(r,hi)]; } }while(0)
;   #define ROT() do{sl_prev=sl_cur;sl_cur=sl_next;sl_next=(sl_next==(NSLOT-1)*SLOTB)?0:sl_next+SLOTB;}while(0)
;     ...
;   int t=1;
;     ...
;   for(;t+5<NT;t+=2){
;     STEP(pB0,pB1,pA0,pA1,t,true,true,true);     WAIT_BAR(2); RESC(); ROT();
;     STEP(pA0,pA1,pB0,pB1,t+1,true,true,true);   WAIT_BAR(2); RESC(); ROT();
;   }
.Lfb_even_s2:
	v_mfma_f32_32x32x16_bf16 v[64:79], v[60:63], v[134:137], v[32:47]
	v_add_u32_e32 v196, s24, v211
	ds_read_b64_tr_b16 v[150:151], v196 offset:24576
	ds_read_b64_tr_b16 v[152:153], v196 offset:25088
	v_add_f32_e32 v222, v96, v222
	v_add_f32_e32 v222, v97, v222
	v_add_f32_e32 v222, v98, v222
	v_add_f32_e32 v222, v99, v222
	v_add_f32_e32 v222, v100, v222
	v_add_f32_e32 v222, v101, v222
	v_cvt_pk_bf16_f32 v142, v96, v97
	v_cvt_pk_bf16_f32 v143, v98, v99
	ds_read_b64_tr_b16 v[146:147], v196 offset:28672
	ds_read_b64_tr_b16 v[148:149], v196 offset:29184
	v_add_f32_e32 v222, v102, v222
	v_add_f32_e32 v222, v103, v222
	v_add_f32_e32 v222, v104, v222
	v_add_f32_e32 v222, v105, v222
	v_mfma_f32_32x32x16_bf16 v[48:63], v[174:177], v[134:137], v[32:47]
	v_cvt_pk_bf16_f32 v144, v100, v101
	v_cvt_pk_bf16_f32 v145, v102, v103
	ds_read_b64_tr_b16 v[96:97], v196 offset:25600
	ds_read_b64_tr_b16 v[98:99], v196 offset:26112
	v_mfma_f32_32x32x16_bf16 v[64:79], v[178:181], v[122:125], v[64:79]
	v_add_f32_e32 v222, v106, v222
	v_add_f32_e32 v222, v107, v222
	v_add_f32_e32 v222, v108, v222
	v_add_f32_e32 v222, v109, v222
	v_cvt_pk_bf16_f32 v138, v104, v105
	v_cvt_pk_bf16_f32 v139, v106, v107
	ds_read_b64_tr_b16 v[100:101], v196 offset:29696
	ds_read_b64_tr_b16 v[102:103], v196 offset:30208
	v_mfma_f32_32x32x16_bf16 v[48:63], v[170:173], v[122:125], v[48:63]
	v_exp_f32_e32 v89, v89
	v_add_f32_e32 v222, v110, v222
	v_add_f32_e32 v222, v111, v222
	v_cvt_pk_bf16_f32 v140, v108, v109
	v_cvt_pk_bf16_f32 v141, v110, v111
	ds_read_b64_tr_b16 v[104:105], v196 offset:26624
	ds_read_b64_tr_b16 v[106:107], v196 offset:27136
	v_mfma_f32_32x32x16_bf16 v[64:79], v[166:169], v[118:121], v[64:79]
	v_exp_f32_e32 v90, v90
	v_exp_f32_e32 v91, v91
	v_cvt_pk_bf16_f32 v130, v80, v81
	v_cvt_pk_bf16_f32 v131, v82, v83
	ds_read_b64_tr_b16 v[80:81], v196 offset:30720
	ds_read_b64_tr_b16 v[82:83], v196 offset:31232
	v_mfma_f32_32x32x16_bf16 v[48:63], v[162:165], v[118:121], v[48:63]
	v_exp_f32_e32 v92, v92
	v_exp_f32_e32 v93, v93
	v_cvt_pk_bf16_f32 v132, v84, v85
	v_cvt_pk_bf16_f32 v133, v86, v87
	ds_read_b64_tr_b16 v[84:85], v196 offset:27648
	ds_read_b64_tr_b16 v[86:87], v196 offset:28160
	v_mfma_f32_32x32x16_bf16 v[64:79], v[158:161], v[114:117], v[64:79]
	v_exp_f32_e32 v94, v94
	v_exp_f32_e32 v95, v95
	v_cvt_pk_bf16_f32 v126, v88, v89
	v_cvt_pk_bf16_f32 v127, v90, v91
	ds_read_b64_tr_b16 v[88:89], v196 offset:31744
	ds_read_b64_tr_b16 v[90:91], v196 offset:32256
	v_mfma_f32_32x32x16_bf16 v[48:63], v[154:157], v[114:117], v[48:63]
	v_cvt_pk_bf16_f32 v128, v92, v93
	v_cvt_pk_bf16_f32 v129, v94, v95
	s_add_i32 m0, s13, s69
	s_nop 0
	global_load_lds_dwordx4 v188, s[2:3]
	s_add_i32 m0, s72, s70
	s_add_u32 s2, s2, 0x58000
	global_load_lds_dwordx4 v186, s[26:27]
	s_addc_u32 s3, s3, 0
	s_add_u32 s26, s26, 0x58000
	s_addc_u32 s27, s27, 0
	s_waitcnt lgkmcnt(8)
	v_mfma_f32_32x32x16_bf16 v[16:31], v[142:145], v[150:153], v[16:31]
	v_exp_f32_e32 v64, v64
	v_exp_f32_e32 v65, v65
	v_exp_f32_e32 v66, v66
	v_exp_f32_e32 v67, v67
	v_mfma_f32_32x32x16_bf16 v[0:15], v[142:145], v[146:149], v[0:15]
	v_exp_f32_e32 v68, v68
	v_exp_f32_e32 v69, v69
	v_exp_f32_e32 v70, v70
	v_add_u32_e32 v92, s72, v210
	ds_read_b128 v[174:177], v92
	ds_read_b128 v[170:173], v92 offset:512
	v_mfma_f32_32x32x16_bf16 v[16:31], v[138:141], v[96:99], v[16:31]
	v_exp_f32_e32 v71, v71
	v_exp_f32_e32 v72, v72
	v_exp_f32_e32 v73, v73
	ds_read_b128 v[166:169], v92 offset:2048
	ds_read_b128 v[162:165], v92 offset:2560
	v_mfma_f32_32x32x16_bf16 v[0:15], v[138:141], v[100:103], v[0:15]
	v_exp_f32_e32 v74, v74
	v_exp_f32_e32 v75, v75
	v_exp_f32_e32 v76, v76
	ds_read_b128 v[158:161], v92 offset:4096
	ds_read_b128 v[154:157], v92 offset:4608
	s_waitcnt lgkmcnt(6)
	v_mfma_f32_32x32x16_bf16 v[16:31], v[130:133], v[104:107], v[16:31]
	v_exp_f32_e32 v77, v77
	v_exp_f32_e32 v78, v78
	v_exp_f32_e32 v79, v79
	ds_read_b128 v[150:153], v92 offset:6144
	ds_read_b128 v[146:149], v92 offset:6656
	v_mfma_f32_32x32x16_bf16 v[0:15], v[130:133], v[80:83], v[0:15]
	v_exp_f32_e32 v48, v48
	v_exp_f32_e32 v49, v49
	v_exp_f32_e32 v50, v50
	v_mfma_f32_32x32x16_bf16 v[16:31], v[126:129], v[84:87], v[16:31]
	v_exp_f32_e32 v51, v51
	v_exp_f32_e32 v52, v52
	v_exp_f32_e32 v53, v53
	v_mfma_f32_32x32x16_bf16 v[0:15], v[126:129], v[88:91], v[0:15]
	v_exp_f32_e32 v54, v54
	v_exp_f32_e32 v55, v55
	v_exp_f32_e32 v56, v56
	s_add_i32 s0, s72, 0x2000
	s_cmpk_lg_i32 s72, 0x4000
	s_cselect_b32 s74, s0, 0
	s_add_i32 s0, s75, 2
	s_cmp_ge_u32 s0, s71
	s_mov_b32 s75, s0
	s_mov_b32 s0, s13
	s_mov_b32 s24, s72
	s_mov_b32 s13, s74
	s_waitcnt vmcnt(2) lgkmcnt(0)
	s_barrier
	s_cbranch_scc0 .Lfb_even
	s_mov_b32 s13, s0
	s_add_i32 s75, s75, -2
	v_mov_b32_e32 v223, v222
	v_exp_f32_e32 v57, v57
	v_exp_f32_e32 v58, v58
	v_exp_f32_e32 v59, v59
	v_exp_f32_e32 v60, v60
	v_exp_f32_e32 v61, v61
	v_exp_f32_e32 v62, v62
	v_exp_f32_e32 v63, v63
	s_branch .LBB0_1231
.Lfb_odd_entry:
	v_mfma_f32_32x32x16_bf16 v[96:111], v[174:177], v[134:137], v[32:47]
	v_add_u32_e32 v183, s0, v211
	ds_read_b64_tr_b16 v[178:179], v183 offset:24576
	ds_read_b64_tr_b16 v[180:181], v183 offset:25088
	v_cvt_pk_bf16_f32 v142, v64, v65
	v_cvt_pk_bf16_f32 v143, v66, v67
	ds_read_b64_tr_b16 v[174:175], v183 offset:28672
	ds_read_b64_tr_b16 v[176:177], v183 offset:29184
	v_mfma_f32_32x32x16_bf16 v[80:95], v[170:173], v[134:137], v[32:47]
	v_cvt_pk_bf16_f32 v144, v68, v69
	v_cvt_pk_bf16_f32 v145, v70, v71
	ds_read_b64_tr_b16 v[64:65], v183 offset:25600
	ds_read_b64_tr_b16 v[66:67], v183 offset:26112
	v_mfma_f32_32x32x16_bf16 v[96:111], v[166:169], v[122:125], v[96:111]
	v_cvt_pk_bf16_f32 v138, v72, v73
	v_cvt_pk_bf16_f32 v139, v74, v75
	ds_read_b64_tr_b16 v[68:69], v183 offset:29696
	ds_read_b64_tr_b16 v[70:71], v183 offset:30208
	v_mfma_f32_32x32x16_bf16 v[80:95], v[162:165], v[122:125], v[80:95]
	v_add_f32_e32 v222, v48, v222
	v_add_f32_e32 v222, v49, v222
	v_cvt_pk_bf16_f32 v140, v76, v77
	v_cvt_pk_bf16_f32 v141, v78, v79
	ds_read_b64_tr_b16 v[72:73], v183 offset:26624
	ds_read_b64_tr_b16 v[74:75], v183 offset:27136
	v_mfma_f32_32x32x16_bf16 v[96:111], v[158:161], v[118:121], v[96:111]
	v_add_f32_e32 v222, v50, v222
	v_add_f32_e32 v222, v51, v222
	v_add_f32_e32 v222, v52, v222
	v_add_f32_e32 v222, v53, v222
	v_cvt_pk_bf16_f32 v130, v48, v49
	v_cvt_pk_bf16_f32 v131, v50, v51
	ds_read_b64_tr_b16 v[48:49], v183 offset:30720
	ds_read_b64_tr_b16 v[50:51], v183 offset:31232
	v_mfma_f32_32x32x16_bf16 v[80:95], v[154:157], v[118:121], v[80:95]
	v_add_f32_e32 v222, v54, v222
	v_add_f32_e32 v222, v55, v222
	v_add_f32_e32 v222, v56, v222
	v_add_f32_e32 v222, v57, v222
	v_cvt_pk_bf16_f32 v132, v52, v53
	v_cvt_pk_bf16_f32 v133, v54, v55
	ds_read_b64_tr_b16 v[52:53], v183 offset:27648
	ds_read_b64_tr_b16 v[54:55], v183 offset:28160
	v_mfma_f32_32x32x16_bf16 v[96:111], v[150:153], v[114:117], v[96:111]
	v_add_f32_e32 v222, v58, v222
	v_add_f32_e32 v222, v59, v222
	v_add_f32_e32 v222, v60, v222
	v_add_f32_e32 v222, v61, v222
	v_cvt_pk_bf16_f32 v126, v56, v57
	v_cvt_pk_bf16_f32 v127, v58, v59
	ds_read_b64_tr_b16 v[56:57], v183 offset:31744
	ds_read_b64_tr_b16 v[58:59], v183 offset:32256
	v_mfma_f32_32x32x16_bf16 v[80:95], v[146:149], v[114:117], v[80:95]
	v_add_f32_e32 v222, v62, v222
	v_add_f32_e32 v222, v63, v222
	v_cvt_pk_bf16_f32 v128, v60, v61
	v_cvt_pk_bf16_f32 v129, v62, v63
	s_add_i32 m0, s24, s69
	s_nop 0
	global_load_lds_dwordx4 v188, s[2:3]
	s_add_i32 m0, s13, s70
	s_add_u32 s2, s2, 0x58000
	global_load_lds_dwordx4 v186, s[26:27]
	s_addc_u32 s3, s3, 0
	s_add_u32 s26, s26, 0x58000
	s_addc_u32 s27, s27, 0
	s_waitcnt lgkmcnt(8)
	v_mfma_f32_32x32x16_bf16 v[16:31], v[142:145], v[178:181], v[16:31]
	v_exp_f32_e32 v96, v96
	v_exp_f32_e32 v97, v97
	v_exp_f32_e32 v98, v98
	v_exp_f32_e32 v99, v99
	v_mfma_f32_32x32x16_bf16 v[0:15], v[142:145], v[174:177], v[0:15]
	v_exp_f32_e32 v100, v100
	v_exp_f32_e32 v101, v101
	v_exp_f32_e32 v102, v102
	v_add_u32_e32 v76, s13, v210
	ds_read_b128 v[60:63], v76
	ds_read_b128 v[174:177], v76 offset:512
	v_mfma_f32_32x32x16_bf16 v[16:31], v[138:141], v[64:67], v[16:31]
	v_exp_f32_e32 v103, v103
	v_exp_f32_e32 v104, v104
	v_exp_f32_e32 v105, v105
	ds_read_b128 v[178:181], v76 offset:2048
	ds_read_b128 v[170:173], v76 offset:2560
	v_mfma_f32_32x32x16_bf16 v[0:15], v[138:141], v[68:71], v[0:15]
	v_exp_f32_e32 v106, v106
	v_exp_f32_e32 v107, v107
	v_exp_f32_e32 v108, v108
	ds_read_b128 v[166:169], v76 offset:4096
	ds_read_b128 v[162:165], v76 offset:4608
	s_waitcnt lgkmcnt(6)
	v_mfma_f32_32x32x16_bf16 v[16:31], v[130:133], v[72:75], v[16:31]
	v_exp_f32_e32 v109, v109
	v_exp_f32_e32 v110, v110
	v_exp_f32_e32 v111, v111
	ds_read_b128 v[158:161], v76 offset:6144
	ds_read_b128 v[154:157], v76 offset:6656
	v_mfma_f32_32x32x16_bf16 v[0:15], v[130:133], v[48:51], v[0:15]
	v_exp_f32_e32 v80, v80
	v_exp_f32_e32 v81, v81
	v_exp_f32_e32 v82, v82
	v_mfma_f32_32x32x16_bf16 v[16:31], v[126:129], v[52:55], v[16:31]
	v_exp_f32_e32 v83, v83
	v_exp_f32_e32 v84, v84
	v_exp_f32_e32 v85, v85
	v_mfma_f32_32x32x16_bf16 v[0:15], v[126:129], v[56:59], v[0:15]
	v_exp_f32_e32 v86, v86
	v_exp_f32_e32 v87, v87
	v_exp_f32_e32 v88, v88
	s_add_i32 s0, s13, 0x2000
	s_cmpk_lg_i32 s13, 0x4000
	s_cselect_b32 s72, s0, 0
	s_waitcnt vmcnt(2) lgkmcnt(0)
	s_barrier
	s_branch .Lfb_odd_s2
.Lfb_odd:
	v_mfma_f32_32x32x16_bf16 v[96:111], v[174:177], v[134:137], v[32:47]
	v_exp_f32_e32 v57, v57
	v_exp_f32_e32 v58, v58
	v_add_u32_e32 v183, s0, v211
	ds_read_b64_tr_b16 v[178:179], v183 offset:24576
	ds_read_b64_tr_b16 v[180:181], v183 offset:25088
	v_cvt_pk_bf16_f32 v142, v64, v65
	v_cvt_pk_bf16_f32 v143, v66, v67
	ds_read_b64_tr_b16 v[174:175], v183 offset:28672
	ds_read_b64_tr_b16 v[176:177], v183 offset:29184
	v_mfma_f32_32x32x16_bf16 v[80:95], v[170:173], v[134:137], v[32:47]
	v_exp_f32_e32 v59, v59
	v_exp_f32_e32 v60, v60
	v_cvt_pk_bf16_f32 v144, v68, v69
	v_cvt_pk_bf16_f32 v145, v70, v71
	ds_read_b64_tr_b16 v[64:65], v183 offset:25600
	ds_read_b64_tr_b16 v[66:67], v183 offset:26112
	v_mfma_f32_32x32x16_bf16 v[96:111], v[166:169], v[122:125], v[96:111]
	v_exp_f32_e32 v61, v61
	v_exp_f32_e32 v62, v62
	v_cvt_pk_bf16_f32 v138, v72, v73
	v_cvt_pk_bf16_f32 v139, v74, v75
	ds_read_b64_tr_b16 v[68:69], v183 offset:29696
	ds_read_b64_tr_b16 v[70:71], v183 offset:30208
	v_mfma_f32_32x32x16_bf16 v[80:95], v[162:165], v[122:125], v[80:95]
	v_exp_f32_e32 v63, v63
	v_add_f32_e32 v222, v48, v222
	v_add_f32_e32 v222, v49, v222
	v_cvt_pk_bf16_f32 v140, v76, v77
	v_cvt_pk_bf16_f32 v141, v78, v79
	ds_read_b64_tr_b16 v[72:73], v183 offset:26624
	ds_read_b64_tr_b16 v[74:75], v183 offset:27136
	v_mfma_f32_32x32x16_bf16 v[96:111], v[158:161], v[118:121], v[96:111]
	v_add_f32_e32 v222, v50, v222
	v_add_f32_e32 v222, v51, v222
	v_add_f32_e32 v222, v52, v222
	v_add_f32_e32 v222, v53, v222
	v_cvt_pk_bf16_f32 v130, v48, v49
	v_cvt_pk_bf16_f32 v131, v50, v51
	ds_read_b64_tr_b16 v[48:49], v183 offset:30720
	ds_read_b64_tr_b16 v[50:51], v183 offset:31232
	v_mfma_f32_32x32x16_bf16 v[80:95], v[154:157], v[118:121], v[80:95]
	v_add_f32_e32 v222, v54, v222
	v_add_f32_e32 v222, v55, v222
	v_add_f32_e32 v222, v56, v222
	v_add_f32_e32 v222, v57, v222
	v_cvt_pk_bf16_f32 v132, v52, v53
	v_cvt_pk_bf16_f32 v133, v54, v55
	ds_read_b64_tr_b16 v[52:53], v183 offset:27648
	ds_read_b64_tr_b16 v[54:55], v183 offset:28160
	v_mfma_f32_32x32x16_bf16 v[96:111], v[150:153], v[114:117], v[96:111]
	v_add_f32_e32 v222, v58, v222
	v_add_f32_e32 v222, v59, v222
	v_add_f32_e32 v222, v60, v222
	v_add_f32_e32 v222, v61, v222
	v_cvt_pk_bf16_f32 v126, v56, v57
	v_cvt_pk_bf16_f32 v127, v58, v59
	ds_read_b64_tr_b16 v[56:57], v183 offset:31744
	ds_read_b64_tr_b16 v[58:59], v183 offset:32256
	v_mfma_f32_32x32x16_bf16 v[80:95], v[146:149], v[114:117], v[80:95]
	v_add_f32_e32 v222, v62, v222
	v_add_f32_e32 v222, v63, v222
	v_cvt_pk_bf16_f32 v128, v60, v61
	v_cvt_pk_bf16_f32 v129, v62, v63
	s_add_i32 m0, s24, s69
	s_nop 0
	global_load_lds_dwordx4 v188, s[2:3]
	s_add_i32 m0, s13, s70
	s_add_u32 s2, s2, 0x58000
	global_load_lds_dwordx4 v186, s[26:27]
	s_addc_u32 s3, s3, 0
	s_add_u32 s26, s26, 0x58000
	s_addc_u32 s27, s27, 0
	s_waitcnt lgkmcnt(8)
	v_mfma_f32_32x32x16_bf16 v[16:31], v[142:145], v[178:181], v[16:31]
	v_exp_f32_e32 v96, v96
	v_exp_f32_e32 v97, v97
	v_exp_f32_e32 v98, v98
	v_exp_f32_e32 v99, v99
	v_mfma_f32_32x32x16_bf16 v[0:15], v[142:145], v[174:177], v[0:15]
	v_exp_f32_e32 v100, v100
	v_exp_f32_e32 v101, v101
	v_exp_f32_e32 v102, v102
	v_add_u32_e32 v76, s13, v210
	ds_read_b128 v[60:63], v76
	ds_read_b128 v[174:177], v76 offset:512
	v_mfma_f32_32x32x16_bf16 v[16:31], v[138:141], v[64:67], v[16:31]
	v_exp_f32_e32 v103, v103
	v_exp_f32_e32 v104, v104
	v_exp_f32_e32 v105, v105
	ds_read_b128 v[178:181], v76 offset:2048
	ds_read_b128 v[170:173], v76 offset:2560
	v_mfma_f32_32x32x16_bf16 v[0:15], v[138:141], v[68:71], v[0:15]
	v_exp_f32_e32 v106, v106
	v_exp_f32_e32 v107, v107
	v_exp_f32_e32 v108, v108
	ds_read_b128 v[166:169], v76 offset:4096
	ds_read_b128 v[162:165], v76 offset:4608
	s_waitcnt lgkmcnt(6)
	v_mfma_f32_32x32x16_bf16 v[16:31], v[130:133], v[72:75], v[16:31]
	v_exp_f32_e32 v109, v109
	v_exp_f32_e32 v110, v110
	v_exp_f32_e32 v111, v111
	ds_read_b128 v[158:161], v76 offset:6144
	ds_read_b128 v[154:157], v76 offset:6656
	v_mfma_f32_32x32x16_bf16 v[0:15], v[130:133], v[48:51], v[0:15]
	v_exp_f32_e32 v80, v80
	v_exp_f32_e32 v81, v81
	v_exp_f32_e32 v82, v82
	v_mfma_f32_32x32x16_bf16 v[16:31], v[126:129], v[52:55], v[16:31]
	v_exp_f32_e32 v83, v83
	v_exp_f32_e32 v84, v84
	v_exp_f32_e32 v85, v85
	v_mfma_f32_32x32x16_bf16 v[0:15], v[126:129], v[56:59], v[0:15]
	v_exp_f32_e32 v86, v86
	v_exp_f32_e32 v87, v87
	v_exp_f32_e32 v88, v88
	s_add_i32 s0, s13, 0x2000
	s_cmpk_lg_i32 s13, 0x4000
	s_cselect_b32 s72, s0, 0
	s_waitcnt vmcnt(2) lgkmcnt(0)
	s_barrier
; #define WAIT_BAR(N) asm volatile("s_waitcnt vmcnt(" #N ") lgkmcnt(0)\n\ts_barrier":::"memory")
;   #define RESC() do{ if(resc){ asm volatile("s_waitcnt lgkmcnt(0)":::"memory"); \
;       _Pragma("unroll") for(int d_=0;d_<2;++d_) _Pragma("unroll") for(int r=0;r<16;++r)o[d_][r]*=wsf[crow(r,hi)]; } }while(0)
;   #define ROT() do{sl_prev=sl_cur;sl_cur=sl_next;sl_next=(sl_next==(NSLOT-1)*SLOTB)?0:sl_next+SLOTB;}while(0)
;     ...
;   int t=1;
;     ...
;   for(;t+5<NT;t+=2){
;     STEP(pB0,pB1,pA0,pA1,t,true,true,true);     WAIT_BAR(2); RESC(); ROT();
;     STEP(pA0,pA1,pB0,pB1,t+1,true,true,true);   WAIT_BAR(2); RESC(); ROT();
;   }
.Lfb_odd_s2:
	v_mfma_f32_32x32x16_bf16 v[64:79], v[60:63], v[134:137], v[32:47]
	v_exp_f32_e32 v89, v89
	v_exp_f32_e32 v90, v90
	v_add_u32_e32 v196, s24, v211
	ds_read_b64_tr_b16 v[150:151], v196 offset:24576
	ds_read_b64_tr_b16 v[152:153], v196 offset:25088
	v_cvt_pk_bf16_f32 v142, v96, v97
	v_cvt_pk_bf16_f32 v143, v98, v99
	ds_read_b64_tr_b16 v[146:147], v196 offset:28672
	ds_read_b64_tr_b16 v[148:149], v196 offset:29184
	v_mfma_f32_32x32x16_bf16 v[48:63], v[174:177], v[134:137], v[32:47]
	v_exp_f32_e32 v91, v91
	v_exp_f32_e32 v92, v92
	v_cvt_pk_bf16_f32 v144, v100, v101
	v_cvt_pk_bf16_f32 v145, v102, v103
	ds_read_b64_tr_b16 v[96:97], v196 offset:25600
	ds_read_b64_tr_b16 v[98:99], v196 offset:26112
	v_mfma_f32_32x32x16_bf16 v[64:79], v[178:181], v[122:125], v[64:79]
	v_exp_f32_e32 v93, v93
	v_exp_f32_e32 v94, v94
	v_cvt_pk_bf16_f32 v138, v104, v105
	v_cvt_pk_bf16_f32 v139, v106, v107
	ds_read_b64_tr_b16 v[100:101], v196 offset:29696
	ds_read_b64_tr_b16 v[102:103], v196 offset:30208
	v_mfma_f32_32x32x16_bf16 v[48:63], v[170:173], v[122:125], v[48:63]
	v_exp_f32_e32 v95, v95
	v_add_f32_e32 v222, v80, v222
	v_add_f32_e32 v222, v81, v222
	v_cvt_pk_bf16_f32 v140, v108, v109
	v_cvt_pk_bf16_f32 v141, v110, v111
	ds_read_b64_tr_b16 v[104:105], v196 offset:26624
	ds_read_b64_tr_b16 v[106:107], v196 offset:27136
	v_mfma_f32_32x32x16_bf16 v[64:79], v[166:169], v[118:121], v[64:79]
	v_add_f32_e32 v222, v82, v222
	v_add_f32_e32 v222, v83, v222
	v_add_f32_e32 v222, v84, v222
	v_add_f32_e32 v222, v85, v222
	v_cvt_pk_bf16_f32 v130, v80, v81
	v_cvt_pk_bf16_f32 v131, v82, v83
	ds_read_b64_tr_b16 v[80:81], v196 offset:30720
	ds_read_b64_tr_b16 v[82:83], v196 offset:31232
	v_mfma_f32_32x32x16_bf16 v[48:63], v[162:165], v[118:121], v[48:63]
	v_add_f32_e32 v222, v86, v222
	v_add_f32_e32 v222, v87, v222
	v_add_f32_e32 v222, v88, v222
	v_add_f32_e32 v222, v89, v222
	v_cvt_pk_bf16_f32 v132, v84, v85
	v_cvt_pk_bf16_f32 v133, v86, v87
	ds_read_b64_tr_b16 v[84:85], v196 offset:27648
	ds_read_b64_tr_b16 v[86:87], v196 offset:28160
	v_mfma_f32_32x32x16_bf16 v[64:79], v[158:161], v[114:117], v[64:79]
	v_add_f32_e32 v222, v90, v222
	v_add_f32_e32 v222, v91, v222
	v_add_f32_e32 v222, v92, v222
	v_add_f32_e32 v222, v93, v222
	v_cvt_pk_bf16_f32 v126, v88, v89
	v_cvt_pk_bf16_f32 v127, v90, v91
	ds_read_b64_tr_b16 v[88:89], v196 offset:31744
	ds_read_b64_tr_b16 v[90:91], v196 offset:32256
	v_mfma_f32_32x32x16_bf16 v[48:63], v[154:157], v[114:117], v[48:63]
	v_add_f32_e32 v222, v94, v222
	v_add_f32_e32 v222, v95, v222
	v_cvt_pk_bf16_f32 v128, v92, v93
	v_cvt_pk_bf16_f32 v129, v94, v95
	s_add_i32 m0, s13, s69
	s_nop 0
	global_load_lds_dwordx4 v188, s[2:3]
	s_add_i32 m0, s72, s70
	s_add_u32 s2, s2, 0x58000
	global_load_lds_dwordx4 v186, s[26:27]
	s_addc_u32 s3, s3, 0
	s_add_u32 s26, s26, 0x58000
	s_addc_u32 s27, s27, 0
	s_waitcnt lgkmcnt(8)
	v_mfma_f32_32x32x16_bf16 v[16:31], v[142:145], v[150:153], v[16:31]
	v_exp_f32_e32 v64, v64
	v_exp_f32_e32 v65, v65
	v_exp_f32_e32 v66, v66
	v_exp_f32_e32 v67, v67
	v_mfma_f32_32x32x16_bf16 v[0:15], v[142:145], v[146:149], v[0:15]
	v_exp_f32_e32 v68, v68
	v_exp_f32_e32 v69, v69
	v_exp_f32_e32 v70, v70
	v_add_u32_e32 v92, s72, v210
	ds_read_b128 v[174:177], v92
	ds_read_b128 v[170:173], v92 offset:512
	v_mfma_f32_32x32x16_bf16 v[16:31], v[138:141], v[96:99], v[16:31]
	v_exp_f32_e32 v71, v71
	v_exp_f32_e32 v72, v72
	v_exp_f32_e32 v73, v73
	ds_read_b128 v[166:169], v92 offset:2048
	ds_read_b128 v[162:165], v92 offset:2560
	v_mfma_f32_32x32x16_bf16 v[0:15], v[138:141], v[100:103], v[0:15]
	v_exp_f32_e32 v74, v74
	v_exp_f32_e32 v75, v75
	v_exp_f32_e32 v76, v76
	ds_read_b128 v[158:161], v92 offset:4096
	ds_read_b128 v[154:157], v92 offset:4608
	s_waitcnt lgkmcnt(6)
	v_mfma_f32_32x32x16_bf16 v[16:31], v[130:133], v[104:107], v[16:31]
	v_exp_f32_e32 v77, v77
	v_exp_f32_e32 v78, v78
	v_exp_f32_e32 v79, v79
	ds_read_b128 v[150:153], v92 offset:6144
	ds_read_b128 v[146:149], v92 offset:6656
	v_mfma_f32_32x32x16_bf16 v[0:15], v[130:133], v[80:83], v[0:15]
	v_exp_f32_e32 v48, v48
	v_exp_f32_e32 v49, v49
	v_exp_f32_e32 v50, v50
	v_mfma_f32_32x32x16_bf16 v[16:31], v[126:129], v[84:87], v[16:31]
	v_exp_f32_e32 v51, v51
	v_exp_f32_e32 v52, v52
	v_exp_f32_e32 v53, v53
	v_mfma_f32_32x32x16_bf16 v[0:15], v[126:129], v[88:91], v[0:15]
	v_exp_f32_e32 v54, v54
	v_exp_f32_e32 v55, v55
	v_exp_f32_e32 v56, v56
	s_add_i32 s0, s72, 0x2000
	s_cmpk_lg_i32 s72, 0x4000
	s_cselect_b32 s74, s0, 0
	s_add_i32 s0, s75, 2
	s_cmp_ge_u32 s0, s71
	s_mov_b32 s75, s0
	s_mov_b32 s0, s13
	s_mov_b32 s24, s72
	s_mov_b32 s13, s74
	s_waitcnt vmcnt(2) lgkmcnt(0)
	s_barrier
	s_cbranch_scc0 .Lfb_odd
	s_mov_b32 s13, s0
	s_add_i32 s75, s75, -2
	v_mov_b32_e32 v223, v222
	v_exp_f32_e32 v57, v57
	v_exp_f32_e32 v58, v58
	v_exp_f32_e32 v59, v59
	v_exp_f32_e32 v60, v60
	v_exp_f32_e32 v61, v61
	v_exp_f32_e32 v62, v62
	v_exp_f32_e32 v63, v63
	s_branch .LBB0_1231
